# speedup vs baseline: 1.0301x; 1.0039x over previous
; template <bool ATRANS = false, bool SWAP = true>
; DEV void gemm_seg(f32x4 (&acc)[4][4], bf16_t* As, bf16_t* Bs, const bf16_t* A, const bf16_t* B, int lda, int ldb,
;                   int K, int arow_lo, int arow_hi) {
;   const int tid = TID(), lane = tid & 63, wid = tid >> 6, wr = wid >> 1, wc = wid & 1;
;   const int fr = lane & 15, fq = lane >> 4;
;   const int lrow = tid >> 3, lk = (tid & 7) * 8;
;   const int tk = tid >> 4, trg = (tid & 15) * 8;
;   const bool av0 = (lrow >= arow_lo) && (lrow < arow_hi), av1 = (lrow + 32 >= arow_lo) && (lrow + 32 < arow_hi),
;              av2 = (lrow + 64 >= arow_lo) && (lrow + 64 < arow_hi), av3 = (lrow + 96 >= arow_lo) && (lrow + 96 < arow_hi);
;   const int c0 = min(max(lrow, arow_lo), arow_hi - 1), c1 = min(max(lrow + 32, arow_lo), arow_hi - 1),
;             c2 = min(max(lrow + 64, arow_lo), arow_hi - 1), c3 = min(max(lrow + 96, arow_lo), arow_hi - 1);
;   const bf16_t* a0 = ATRANS ? A + (long)(tk) * lda + trg : A + (long)c0 * lda + lk;
;   const bf16_t* a1 = ATRANS ? A + (long)(tk + 16) * lda + trg : A + (long)c1 * lda + lk;
;   const bf16_t* a2 = ATRANS ? A + (long)(tk + 32) * lda + trg : A + (long)c2 * lda + lk;
;   const bf16_t* a3 = ATRANS ? A + (long)(tk + 48) * lda + trg : A + (long)c3 * lda + lk;
;   const bf16_t* b0 = B + (long)lrow * ldb + lk;
;   const long bstep = 32L * ldb;
;   const long astep = ATRANS ? (long)lda : 1L;
;   uint4 A0a, A0b, A0c, A0d, B0a, B0b, B0c, B0d;
;   uint4 A1a, A1b, A1c, A1d, B1a, B1b, B1c, B1d;
;   const int so = lrow * LDT + lk;
;   const int sw = lrow * 64 + (((lk >> 3) ^ (lrow & 7)) * 8);
; DEV void phase_win(const Params& p, int layer, int grp, char* smem) {
;     ...
;   for (int it = BID(); it < ntiles; it += NBLK()) {
;     const int tid = TID(), lane = tid & 63, wid = tid >> 6;
;     const int xq = it & 7, jq = it >> 3;
;     const int band = jq / 192, rq = jq % 192;
;     const int tm = 8 * (band * 8 + ((rq & 63) >> 3)) + xq, tn = (rq >> 6) * 8 + (rq & 7);
;     const int r0 = tm * 128;
;     const int sl = r0 / L, t0 = r0 % L;
;     const bf16_t* Ap = p.Hin + ((long)grp * TG + r0) * D;
;     const bf16_t* Bp = p.WinT + (long)layer * INW * D + (long)tn * 128 * D;
;     const bool transposed = (tn >= 8 && tn < 12) || (tn >= 16 && tn < 22);
;     if (transposed) gemm_tile1<false>(smem, Ap, Bp, D, D, D);
;     else gemm_tile1<true>(smem, Ap, Bp, D, D, D);
.LBB0_327:
	v_readlane_b32 s0, v253, 0
	v_readlane_b32 s6, v253, 6
	s_mov_b32 s0, s6
	s_add_i32 s24, s0, s24
	s_cmpk_lt_i32 s24, 0x1e00
	v_readlane_b32 s1, v253, 1
	v_readlane_b32 s2, v253, 2
	v_readlane_b32 s3, v253, 3
	v_readlane_b32 s4, v253, 4
	v_readlane_b32 s5, v253, 5
	v_readlane_b32 s7, v253, 7
	s_cbranch_scc0 .LBB0_373
.LBB0_328:
	s_ashr_i32 s65, s24, 3
	s_mul_hi_i32 s0, s65, 0x2aaaaaab
	s_lshr_b32 s1, s0, 31
	s_ashr_i32 s0, s0, 5
	s_add_i32 s0, s0, s1
	s_mul_i32 s1, s0, 0xc0
	s_sub_i32 s25, s65, s1
	s_lshl_b32 s30, s0, 6
	s_and_b32 s29, s25, 56
	s_and_b32 s95, s24, 7
	s_or_b32 s0, s30, s29
	s_or_b32 s84, s0, s95
	s_ashr_i32 s28, s25, 3
	s_and_b32 s0, s28, -8
	s_and_b32 s1, s25, 7
	s_lshl_b32 s34, s84, 7
	s_or_b32 s18, s0, s1
	s_ashr_i32 s35, s34, 31
	s_add_u32 s60, s12, s34
	s_addc_u32 s61, s13, s35
	s_lshl_b64 s[0:1], s[60:61], 11
	s_add_u32 s0, s70, s0
	s_addc_u32 s1, s71, s1
	s_ashr_i32 s19, s18, 31
	s_lshl_b64 s[2:3], s[18:19], 18
	s_add_u32 s20, s26, s2
	s_addc_u32 s21, s27, s3
	s_and_b32 s2, s18, -4
	s_cmp_lg_u32 s2, 8
	s_cselect_b64 s[2:3], -1, 0
	s_add_i32 s4, s18, -16
	s_cmp_gt_u32 s4, 5
	s_cselect_b64 s[4:5], -1, 0
	s_and_b64 s[92:93], s[2:3], s[4:5]
	v_mov_b32_e32 v144, v166
	s_mov_b64 s[2:3], -1
	s_and_b64 vcc, exec, s[92:93]
	s_cbranch_vccz .LBB0_338
	v_mov_b32_e32 v82, v166
	s_mov_b32 s2, 0x10000
	v_ashrrev_i32_e32 v64, 3, v82
	v_max_i32_e32 v1, 0xffffffe0, v64
	v_med3_i32 v0, v64, 0, v204
	v_add_u32_e32 v1, 32, v1
	v_max_i32_e32 v2, 0xffffffc0, v64
	v_min_u32_e32 v1, 0x7f, v1
	v_add_u32_e32 v2, 64, v2
	v_max_i32_e32 v3, 0xffffffa0, v64
	v_lshlrev_b32_e32 v128, 11, v0
	v_lshlrev_b32_e32 v0, 4, v82
	v_min_u32_e32 v2, 0x7f, v2
	v_add_u32_e32 v3, 0x60, v3
	v_lshl_add_u64 v[146:147], s[0:1], 0, v[128:129]
	v_and_b32_e32 v128, 0x70, v0
	v_lshlrev_b32_e32 v0, 11, v1
	v_mov_b32_e32 v1, v129
	v_min_u32_e32 v3, 0x7f, v3
	v_lshl_add_u64 v[148:149], s[0:1], 0, v[0:1]
	v_lshlrev_b32_e32 v0, 11, v2
	v_lshl_add_u64 v[150:151], s[0:1], 0, v[0:1]
	v_lshlrev_b32_e32 v0, 11, v3
	v_ashrrev_i32_e32 v65, 31, v64
	v_lshl_add_u64 v[152:153], s[0:1], 0, v[0:1]
	v_lshlrev_b64 v[0:1], 11, v[64:65]
	v_lshl_add_u64 v[154:155], s[20:21], 0, v[0:1]
	v_lshl_add_u64 v[74:75], v[154:155], 0, v[128:129]
	v_add_co_u32_e32 v76, vcc, s2, v74
	s_mov_b32 s2, 0x20000
	s_nop 0
	v_addc_co_u32_e32 v77, vcc, 0, v75, vcc
	v_lshl_add_u64 v[66:67], v[146:147], 0, v[128:129]
	v_add_co_u32_e32 v78, vcc, s2, v74
	v_lshl_add_u64 v[68:69], v[148:149], 0, v[128:129]
	v_lshl_add_u64 v[70:71], v[150:151], 0, v[128:129]
	v_lshl_add_u64 v[72:73], v[152:153], 0, v[128:129]
	global_load_dwordx4 v[28:31], v[66:67], off
	global_load_dwordx4 v[36:39], v[68:69], off
	global_load_dwordx4 v[40:43], v[70:71], off
	global_load_dwordx4 v[44:47], v[72:73], off
	v_addc_co_u32_e32 v79, vcc, 0, v75, vcc
	s_mov_b32 s2, 0x30000
	v_add_co_u32_e32 v80, vcc, s2, v74
	global_load_dwordx4 v[48:51], v[74:75], off
	global_load_dwordx4 v[52:55], v[76:77], off
	v_addc_co_u32_e32 v81, vcc, 0, v75, vcc
	global_load_dwordx4 v[56:59], v[78:79], off
	global_load_dwordx4 v[60:63], v[80:81], off
	s_movk_i32 s8, 0x80
	v_add_u32_e32 v1, 32, v64
	v_cmp_gt_u32_e64 s[4:5], s8, v1
	v_add_u32_e32 v1, 64, v64
	v_lshlrev_b32_e32 v0, 3, v82
	v_cmp_gt_u32_e64 s[6:7], s8, v1
	v_add_u32_e32 v1, 0x60, v64
	v_lshrrev_b32_e32 v65, 4, v82
	v_bfe_u32 v83, v82, 4, 2
	v_cmp_gt_u32_e64 s[2:3], s8, v64
	v_cmp_gt_u32_e64 s[8:9], s8, v1
	s_mov_b32 s19, 0
	v_bitop3_b32 v84, v0, 56, v82 bitop3:0x48
	global_load_dwordx4 v[0:3], v[66:67], off offset:128
	global_load_dwordx4 v[4:7], v[68:69], off offset:128
	global_load_dwordx4 v[8:11], v[70:71], off offset:128
	global_load_dwordx4 v[12:15], v[72:73], off offset:128
	global_load_dwordx4 v[16:19], v[74:75], off offset:128
	global_load_dwordx4 v[20:23], v[76:77], off offset:128
	global_load_dwordx4 v[24:27], v[78:79], off offset:128
	global_load_dwordx4 v[32:35], v[80:81], off offset:128
	v_lshlrev_b32_e32 v84, 1, v84
	s_waitcnt lgkmcnt(0)
	s_barrier
; template <bool ATRANS = false, bool SWAP = true>
; DEV void gemm_seg(f32x4 (&acc)[4][4], bf16_t* As, bf16_t* Bs, const bf16_t* A, const bf16_t* B, int lda, int ldb,
;                   int K, int arow_lo, int arow_hi) {
;     ...
;   GLOAD(0, 0);
;   GLOAD(1, 1);
;   STAB(0, 0);
;   GLOAD(0, 2);
; DEV void acc_zero(f32x4 (&acc)[4][4]) {
; #pragma unroll
;   for (int m = 0; m < 4; ++m)
; #pragma unroll
;     for (int n = 0; n < 4; ++n) acc[m][n] = f32x4{0.f, 0.f, 0.f, 0.f};
	s_waitcnt vmcnt(15)
	v_cndmask_b32_e64 v28, 0, v28, s[2:3]
	v_cndmask_b32_e64 v29, 0, v29, s[2:3]
	v_cndmask_b32_e64 v30, 0, v30, s[2:3]
	v_cndmask_b32_e64 v31, 0, v31, s[2:3]
	v_lshl_or_b32 v133, v64, 7, v84
	ds_write_b128 v133, v[28:31]
	s_waitcnt vmcnt(14)
	v_cndmask_b32_e64 v28, 0, v36, s[4:5]
	v_cndmask_b32_e64 v29, 0, v37, s[4:5]
	v_cndmask_b32_e64 v30, 0, v38, s[4:5]
	v_cndmask_b32_e64 v31, 0, v39, s[4:5]
	ds_write_b128 v133, v[28:31] offset:4096
	s_waitcnt vmcnt(13)
	v_cndmask_b32_e64 v28, 0, v40, s[6:7]
	v_cndmask_b32_e64 v29, 0, v41, s[6:7]
	v_cndmask_b32_e64 v30, 0, v42, s[6:7]
	v_cndmask_b32_e64 v31, 0, v43, s[6:7]
	ds_write_b128 v133, v[28:31] offset:8192
	s_waitcnt vmcnt(12)
	v_cndmask_b32_e64 v28, 0, v44, s[8:9]
	v_cndmask_b32_e64 v29, 0, v45, s[8:9]
	v_cndmask_b32_e64 v30, 0, v46, s[8:9]
	v_cndmask_b32_e64 v31, 0, v47, s[8:9]
	ds_write_b128 v133, v[28:31] offset:12288
	s_waitcnt vmcnt(11)
	ds_write_b128 v133, v[48:51] offset:36864
	s_waitcnt vmcnt(10)
	ds_write_b128 v133, v[52:55] offset:40960
	s_waitcnt vmcnt(9)
	ds_write_b128 v133, v[56:59] offset:45056
	s_waitcnt vmcnt(8)
	ds_write_b128 v133, v[60:63] offset:49152
	s_waitcnt lgkmcnt(0)
	s_barrier
	global_load_dwordx4 v[28:31], v[66:67], off offset:256
	global_load_dwordx4 v[36:39], v[68:69], off offset:256
	global_load_dwordx4 v[40:43], v[70:71], off offset:256
	global_load_dwordx4 v[44:47], v[72:73], off offset:256
	global_load_dwordx4 v[48:51], v[74:75], off offset:256
	global_load_dwordx4 v[52:55], v[76:77], off offset:256
	global_load_dwordx4 v[56:59], v[78:79], off offset:256
	global_load_dwordx4 v[60:63], v[80:81], off offset:256
	v_and_b32_e32 v66, 7, v82
	v_lshlrev_b32_e32 v67, 7, v82
	v_lshlrev_b32_e32 v64, 6, v82
	v_and_b32_e32 v68, 0x2000, v67
	v_bitop3_b32 v65, v65, v66, 3 bitop3:0x6c
	v_and_b32_e32 v67, 0x780, v67
	v_and_b32_e32 v64, 0xffffe000, v64
	v_lshl_or_b32 v65, v65, 4, v67
	v_or_b32_e32 v137, v64, v65
	v_or_b32_e32 v139, v68, v65
	v_bitop3_b32 v65, v83, v66, 4 bitop3:0x36
	v_lshl_or_b32 v65, v65, 4, v67
	v_or_b32_e32 v145, v64, v65
	v_mov_b32_e32 v64, 0
	v_add_u32_e32 v135, 0xd800, v133
	v_or_b32_e32 v207, v68, v65
	v_lshlrev_b32_e32 v128, 4, v66
	v_mov_b32_e32 v65, v64
	v_mov_b32_e32 v66, v64
	v_mov_b32_e32 v67, v64
	v_mov_b32_e32 v68, v64
	v_mov_b32_e32 v69, v64
	v_mov_b32_e32 v70, v64
	v_mov_b32_e32 v71, v64
	v_mov_b32_e32 v72, v64
	v_mov_b32_e32 v73, v64
	v_mov_b32_e32 v74, v64
	v_mov_b32_e32 v75, v64
	v_mov_b32_e32 v76, v64
	v_mov_b32_e32 v77, v64
	v_mov_b32_e32 v78, v64
	v_mov_b32_e32 v79, v64
	v_mov_b32_e32 v80, v64
	v_mov_b32_e32 v81, v64
	v_mov_b32_e32 v82, v64
	v_mov_b32_e32 v83, v64
	v_mov_b32_e32 v84, v64
	v_mov_b32_e32 v85, v64
	v_mov_b32_e32 v86, v64
	v_mov_b32_e32 v87, v64
	v_mov_b32_e32 v88, v64
	v_mov_b32_e32 v89, v64
	v_mov_b32_e32 v90, v64
	v_mov_b32_e32 v91, v64
	v_mov_b32_e32 v92, v64
	v_mov_b32_e32 v93, v64
	v_mov_b32_e32 v94, v64
	v_mov_b32_e32 v95, v64
	v_mov_b32_e32 v96, v64
	v_mov_b32_e32 v97, v64
	v_mov_b32_e32 v98, v64
	v_mov_b32_e32 v99, v64
	v_mov_b32_e32 v100, v64
	v_mov_b32_e32 v101, v64
	v_mov_b32_e32 v102, v64
	v_mov_b32_e32 v103, v64
	v_mov_b32_e32 v104, v64
	v_mov_b32_e32 v105, v64
	v_mov_b32_e32 v106, v64
	v_mov_b32_e32 v107, v64
	v_mov_b32_e32 v108, v64
	v_mov_b32_e32 v109, v64
	v_mov_b32_e32 v110, v64
	v_mov_b32_e32 v111, v64
	v_mov_b32_e32 v112, v64
	v_mov_b32_e32 v113, v64
	v_mov_b32_e32 v114, v64
	v_mov_b32_e32 v115, v64
	v_mov_b32_e32 v116, v64
	v_mov_b32_e32 v117, v64
	v_mov_b32_e32 v118, v64
	v_mov_b32_e32 v119, v64
	v_mov_b32_e32 v120, v64
	v_mov_b32_e32 v121, v64
	v_mov_b32_e32 v122, v64
	v_mov_b32_e32 v123, v64
	v_mov_b32_e32 v124, v64
	v_mov_b32_e32 v125, v64
	v_mov_b32_e32 v126, v64
	v_mov_b32_e32 v127, v64
	s_branch .LBB0_331

; DEV int TID() { int t = threadIdx.x; asm volatile("" : "+v"(t)); return t; }
; template <bool ATRANS = false, bool SWAP = true>
; DEV void gemm_seg(f32x4 (&acc)[4][4], bf16_t* As, bf16_t* Bs, const bf16_t* A, const bf16_t* B, int lda, int ldb,
;                   int K, int arow_lo, int arow_hi) {
;   const int tid = TID(), lane = tid & 63, wid = tid >> 6, wr = wid >> 1, wc = wid & 1;
;   const int fr = lane & 15, fq = lane >> 4;
;   const int lrow = tid >> 3, lk = (tid & 7) * 8;
;   const int tk = tid >> 4, trg = (tid & 15) * 8;
;   const bool av0 = (lrow >= arow_lo) && (lrow < arow_hi), av1 = (lrow + 32 >= arow_lo) && (lrow + 32 < arow_hi),
;              av2 = (lrow + 64 >= arow_lo) && (lrow + 64 < arow_hi), av3 = (lrow + 96 >= arow_lo) && (lrow + 96 < arow_hi);
;   const int c0 = min(max(lrow, arow_lo), arow_hi - 1), c1 = min(max(lrow + 32, arow_lo), arow_hi - 1),
;             c2 = min(max(lrow + 64, arow_lo), arow_hi - 1), c3 = min(max(lrow + 96, arow_lo), arow_hi - 1);
;   const bf16_t* a0 = ATRANS ? A + (long)(tk) * lda + trg : A + (long)c0 * lda + lk;
;   const bf16_t* a1 = ATRANS ? A + (long)(tk + 16) * lda + trg : A + (long)c1 * lda + lk;
;   const bf16_t* a2 = ATRANS ? A + (long)(tk + 32) * lda + trg : A + (long)c2 * lda + lk;
;   const bf16_t* a3 = ATRANS ? A + (long)(tk + 48) * lda + trg : A + (long)c3 * lda + lk;
;   const bf16_t* b0 = B + (long)lrow * ldb + lk;
;   const long bstep = 32L * ldb;
;   const long astep = ATRANS ? (long)lda : 1L;
;   uint4 A0a, A0b, A0c, A0d, B0a, B0b, B0c, B0d;
;   uint4 A1a, A1b, A1c, A1d, B1a, B1b, B1c, B1d;
;   const int so = lrow * LDT + lk;
;   const int sw = lrow * 64 + (((lk >> 3) ^ (lrow & 7)) * 8);
;   const int nk = K / BK;
;   const unsigned am0 = av0 ? 0xffffffffu : 0u, am1 = av1 ? 0xffffffffu : 0u, am2 = av2 ? 0xffffffffu : 0u,
;                  am3 = av3 ? 0xffffffffu : 0u;
; DEV void acc_zero(f32x4 (&acc)[4][4]) {
; #pragma unroll
;   for (int m = 0; m < 4; ++m)
; #pragma unroll
;     for (int n = 0; n < 4; ++n) acc[m][n] = f32x4{0.f, 0.f, 0.f, 0.f};
.LBB0_338:
	s_and_b64 vcc, exec, s[2:3]
	s_cbranch_vccz .LBB0_348
	v_mov_b32_e32 v82, v166
	s_mov_b32 s19, 0
	v_ashrrev_i32_e32 v64, 3, v82
	v_add_u32_e32 v2, 32, v64
	v_med3_i32 v0, v64, 0, v204
	v_add_u32_e32 v3, 64, v64
	v_med3_i32 v1, v2, 0, v204
	v_lshlrev_b32_e32 v128, 11, v0
	v_lshlrev_b32_e32 v0, 4, v82
	s_waitcnt vmcnt(6)
	v_add_u32_e32 v4, 0x60, v64
	v_med3_i32 v5, v3, 0, v204
	v_lshl_add_u64 v[146:147], s[0:1], 0, v[128:129]
	v_and_b32_e32 v128, 0x70, v0
	v_lshlrev_b32_e32 v0, 11, v1
	v_mov_b32_e32 v1, v129
	v_med3_i32 v6, v4, 0, v204
	v_lshl_add_u64 v[148:149], s[0:1], 0, v[0:1]
	v_lshlrev_b32_e32 v0, 11, v5
	v_lshl_add_u64 v[150:151], s[0:1], 0, v[0:1]
	v_lshlrev_b32_e32 v0, 11, v6
	v_ashrrev_i32_e32 v65, 31, v64
	v_lshl_add_u64 v[152:153], s[0:1], 0, v[0:1]
	v_lshlrev_b64 v[0:1], 11, v[64:65]
	v_lshl_add_u64 v[154:155], s[20:21], 0, v[0:1]
	v_lshl_add_u64 v[74:75], v[154:155], 0, v[128:129]
	s_mov_b32 s0, 0x10000
	v_add_co_u32_e32 v76, vcc, s0, v74
	s_mov_b32 s0, 0x20000
	s_nop 0
	v_addc_co_u32_e32 v77, vcc, 0, v75, vcc
	v_lshl_add_u64 v[66:67], v[146:147], 0, v[128:129]
	v_add_co_u32_e32 v78, vcc, s0, v74
	v_lshl_add_u64 v[68:69], v[148:149], 0, v[128:129]
	v_lshl_add_u64 v[70:71], v[150:151], 0, v[128:129]
	v_lshl_add_u64 v[72:73], v[152:153], 0, v[128:129]
	global_load_dwordx4 v[32:35], v[66:67], off
	global_load_dwordx4 v[36:39], v[68:69], off
	global_load_dwordx4 v[40:43], v[70:71], off
	global_load_dwordx4 v[44:47], v[72:73], off
	v_addc_co_u32_e32 v79, vcc, 0, v75, vcc
	s_mov_b32 s0, 0x30000
	v_add_co_u32_e32 v80, vcc, s0, v74
	global_load_dwordx4 v[48:51], v[74:75], off
	global_load_dwordx4 v[52:55], v[76:77], off
	v_addc_co_u32_e32 v81, vcc, 0, v75, vcc
	global_load_dwordx4 v[56:59], v[78:79], off
	global_load_dwordx4 v[60:63], v[80:81], off
	v_lshlrev_b32_e32 v0, 3, v82
	s_movk_i32 s0, 0x80
	v_lshrrev_b32_e32 v65, 4, v82
	v_bfe_u32 v83, v82, 4, 2
	v_cmp_gt_u32_e64 s[2:3], s0, v64
	v_cmp_gt_u32_e64 s[4:5], s0, v2
	v_cmp_gt_u32_e64 s[6:7], s0, v3
	v_cmp_gt_u32_e64 s[8:9], s0, v4
	v_bitop3_b32 v84, v0, 56, v82 bitop3:0x48
	global_load_dwordx4 v[0:3], v[66:67], off offset:128
	global_load_dwordx4 v[4:7], v[68:69], off offset:128
	global_load_dwordx4 v[8:11], v[70:71], off offset:128
	global_load_dwordx4 v[12:15], v[72:73], off offset:128
	global_load_dwordx4 v[16:19], v[74:75], off offset:128
	global_load_dwordx4 v[20:23], v[76:77], off offset:128
	global_load_dwordx4 v[24:27], v[78:79], off offset:128
	global_load_dwordx4 v[28:31], v[80:81], off offset:128
	v_lshlrev_b32_e32 v84, 1, v84
	s_waitcnt lgkmcnt(0)
	s_barrier
	s_waitcnt vmcnt(15)
	v_cndmask_b32_e64 v32, 0, v32, s[2:3]
	v_cndmask_b32_e64 v33, 0, v33, s[2:3]
	v_cndmask_b32_e64 v34, 0, v34, s[2:3]
	v_cndmask_b32_e64 v35, 0, v35, s[2:3]
	v_lshl_or_b32 v133, v64, 7, v84
	ds_write_b128 v133, v[32:35]
	s_waitcnt vmcnt(14)
	v_cndmask_b32_e64 v32, 0, v36, s[4:5]
	v_cndmask_b32_e64 v33, 0, v37, s[4:5]
	v_cndmask_b32_e64 v34, 0, v38, s[4:5]
	v_cndmask_b32_e64 v35, 0, v39, s[4:5]
	ds_write_b128 v133, v[32:35] offset:4096
	s_waitcnt vmcnt(13)
	v_cndmask_b32_e64 v32, 0, v40, s[6:7]
	v_cndmask_b32_e64 v33, 0, v41, s[6:7]
	v_cndmask_b32_e64 v34, 0, v42, s[6:7]
	v_cndmask_b32_e64 v35, 0, v43, s[6:7]
	ds_write_b128 v133, v[32:35] offset:8192
	s_waitcnt vmcnt(12)
	v_cndmask_b32_e64 v32, 0, v44, s[8:9]
	v_cndmask_b32_e64 v33, 0, v45, s[8:9]
	v_cndmask_b32_e64 v34, 0, v46, s[8:9]
	v_cndmask_b32_e64 v35, 0, v47, s[8:9]
	ds_write_b128 v133, v[32:35] offset:12288
	s_waitcnt vmcnt(11)
	ds_write_b128 v133, v[48:51] offset:36864
	s_waitcnt vmcnt(10)
	ds_write_b128 v133, v[52:55] offset:40960
	s_waitcnt vmcnt(9)
	ds_write_b128 v133, v[56:59] offset:45056
	s_waitcnt vmcnt(8)
	ds_write_b128 v133, v[60:63] offset:49152
	s_waitcnt lgkmcnt(0)
	s_barrier
	global_load_dwordx4 v[60:63], v[80:81], off offset:256
	global_load_dwordx4 v[56:59], v[78:79], off offset:256
	global_load_dwordx4 v[52:55], v[76:77], off offset:256
	global_load_dwordx4 v[48:51], v[74:75], off offset:256
	global_load_dwordx4 v[44:47], v[72:73], off offset:256
	global_load_dwordx4 v[40:43], v[70:71], off offset:256
	global_load_dwordx4 v[36:39], v[68:69], off offset:256
	global_load_dwordx4 v[32:35], v[66:67], off offset:256
	v_and_b32_e32 v66, 7, v82
	v_lshlrev_b32_e32 v67, 7, v82
	v_lshlrev_b32_e32 v64, 6, v82
	v_and_b32_e32 v68, 0x2000, v67
	v_bitop3_b32 v65, v65, v66, 3 bitop3:0x6c
	v_and_b32_e32 v67, 0x780, v67
	v_and_b32_e32 v64, 0xffffe000, v64
	v_lshl_or_b32 v65, v65, 4, v67
	v_or_b32_e32 v137, v64, v65
	v_or_b32_e32 v139, v68, v65
	v_bitop3_b32 v65, v83, v66, 4 bitop3:0x36
	v_lshl_or_b32 v65, v65, 4, v67
	v_or_b32_e32 v145, v64, v65
	v_mov_b32_e32 v64, 0
	v_add_u32_e32 v135, 0xd800, v133
	v_or_b32_e32 v207, v68, v65
	v_lshlrev_b32_e32 v128, 4, v66
	v_mov_b32_e32 v65, v64
	v_mov_b32_e32 v66, v64
	v_mov_b32_e32 v67, v64
	v_mov_b32_e32 v68, v64
	v_mov_b32_e32 v69, v64
	v_mov_b32_e32 v70, v64
	v_mov_b32_e32 v71, v64
	v_mov_b32_e32 v72, v64
	v_mov_b32_e32 v73, v64
	v_mov_b32_e32 v74, v64
	v_mov_b32_e32 v75, v64
	v_mov_b32_e32 v76, v64
	v_mov_b32_e32 v77, v64
	v_mov_b32_e32 v78, v64
	v_mov_b32_e32 v79, v64
	v_mov_b32_e32 v80, v64
	v_mov_b32_e32 v81, v64
	v_mov_b32_e32 v82, v64
	v_mov_b32_e32 v83, v64
	v_mov_b32_e32 v84, v64
	v_mov_b32_e32 v85, v64
	v_mov_b32_e32 v86, v64
	v_mov_b32_e32 v87, v64
	v_mov_b32_e32 v88, v64
	v_mov_b32_e32 v89, v64
	v_mov_b32_e32 v90, v64
	v_mov_b32_e32 v91, v64
	v_mov_b32_e32 v92, v64
	v_mov_b32_e32 v93, v64
	v_mov_b32_e32 v94, v64
	v_mov_b32_e32 v95, v64
	v_mov_b32_e32 v96, v64
	v_mov_b32_e32 v97, v64
	v_mov_b32_e32 v98, v64
	v_mov_b32_e32 v99, v64
	v_mov_b32_e32 v100, v64
	v_mov_b32_e32 v101, v64
	v_mov_b32_e32 v102, v64
	v_mov_b32_e32 v103, v64
	v_mov_b32_e32 v104, v64
	v_mov_b32_e32 v105, v64
	v_mov_b32_e32 v106, v64
	v_mov_b32_e32 v107, v64
	v_mov_b32_e32 v108, v64
	v_mov_b32_e32 v109, v64
	v_mov_b32_e32 v110, v64
	v_mov_b32_e32 v111, v64
	v_mov_b32_e32 v112, v64
	v_mov_b32_e32 v113, v64
	v_mov_b32_e32 v114, v64
	v_mov_b32_e32 v115, v64
	v_mov_b32_e32 v116, v64
	v_mov_b32_e32 v117, v64
	v_mov_b32_e32 v118, v64
	v_mov_b32_e32 v119, v64
	v_mov_b32_e32 v120, v64
	v_mov_b32_e32 v121, v64
	v_mov_b32_e32 v122, v64
	v_mov_b32_e32 v123, v64
	v_mov_b32_e32 v124, v64
	v_mov_b32_e32 v125, v64
	v_mov_b32_e32 v126, v64
	v_mov_b32_e32 v127, v64
	s_branch .LBB0_341

; template <bool ATRANS = false, bool SWAP = true>
; DEV void gemm_seg(f32x4 (&acc)[4][4], bf16_t* As, bf16_t* Bs, const bf16_t* A, const bf16_t* B, int lda, int ldb,
;                   int K, int arow_lo, int arow_hi) {
;   const int tid = TID(), lane = tid & 63, wid = tid >> 6, wr = wid >> 1, wc = wid & 1;
;   const int fr = lane & 15, fq = lane >> 4;
;   const int lrow = tid >> 3, lk = (tid & 7) * 8;
;   const int tk = tid >> 4, trg = (tid & 15) * 8;
;   const bool av0 = (lrow >= arow_lo) && (lrow < arow_hi), av1 = (lrow + 32 >= arow_lo) && (lrow + 32 < arow_hi),
;              av2 = (lrow + 64 >= arow_lo) && (lrow + 64 < arow_hi), av3 = (lrow + 96 >= arow_lo) && (lrow + 96 < arow_hi);
;   const int c0 = min(max(lrow, arow_lo), arow_hi - 1), c1 = min(max(lrow + 32, arow_lo), arow_hi - 1),
;             c2 = min(max(lrow + 64, arow_lo), arow_hi - 1), c3 = min(max(lrow + 96, arow_lo), arow_hi - 1);
;   const bf16_t* a0 = ATRANS ? A + (long)(tk) * lda + trg : A + (long)c0 * lda + lk;
;   const bf16_t* a1 = ATRANS ? A + (long)(tk + 16) * lda + trg : A + (long)c1 * lda + lk;
;   const bf16_t* a2 = ATRANS ? A + (long)(tk + 32) * lda + trg : A + (long)c2 * lda + lk;
;   const bf16_t* a3 = ATRANS ? A + (long)(tk + 48) * lda + trg : A + (long)c3 * lda + lk;
;   const bf16_t* b0 = B + (long)lrow * ldb + lk;
;   const long bstep = 32L * ldb;
;   const long astep = ATRANS ? (long)lda : 1L;
;   uint4 A0a, A0b, A0c, A0d, B0a, B0b, B0c, B0d;
;   uint4 A1a, A1b, A1c, A1d, B1a, B1b, B1c, B1d;
;   const int so = lrow * LDT + lk;
;   const int sw = lrow * 64 + (((lk >> 3) ^ (lrow & 7)) * 8);
;   const int nk = K / BK;
;   const unsigned am0 = av0 ? 0xffffffffu : 0u, am1 = av1 ? 0xffffffffu : 0u, am2 = av2 ? 0xffffffffu : 0u,
;                  am3 = av3 ? 0xffffffffu : 0u;
; DEV void phase_up(const Params& p, int layer, char* smem) {
;     ...
;   for (int it = BID(); it < ntiles; it += NBLK()) {
;     const int tid = TID(), lane = tid & 63, wid = tid >> 6;
;     const int tn = it % 44, tmm = it / 44;
;     const int sl = tmm / MT, tm = tmm % MT;
;     const int tstart = 126 * tm - 1;
;     const int lo = max(0, -tstart), hi = min(128, L - tstart);
;     gemm_tile1<true>(smem, p.Hwk + ((long)sl * L + tstart) * D, p.WupT + (long)layer * 2 * DFF * D + (long)tn * 128 * D,
;                      D, D, D, lo, hi);
.LBB0_820:
	s_mov_b32 s0, s30
	s_add_i32 s20, s0, s20
.LBB0_821:
	s_cmpk_gt_i32 s20, 0x38b7
	s_cbranch_scc1 .LBB0_838
	s_lshr_b32 s0, s20, 3
	s_mul_i32 s1, s0, 0x1746
	s_lshr_b32 s1, s1, 16
	s_mul_i32 s2, s1, 11
	s_sub_i32 s0, s0, s2
	s_mul_i32 s1, s1, 88
	s_add_i32 s0, s0, s1
	s_and_b32 s1, s20, 3
	s_mul_i32 s1, s1, 11
	s_add_i32 s0, s0, s1
	s_bfe_u32 s1, s20, 0x10002
	s_mul_i32 s1, s1, 44
	s_add_i32 s2, s0, s1
	s_mul_hi_i32 s0, s2, 0x2e8ba2e9
	s_lshr_b32 s1, s0, 31
	s_ashr_i32 s0, s0, 3
	s_add_i32 s1, s0, s1
	s_mul_i32 s0, s1, 44
	s_sub_i32 s60, s2, s0
	s_mul_hi_i32 s0, s2, 0xb48a39d5
	s_add_i32 s0, s0, s2
	s_lshr_b32 s2, s0, 31
	s_ashr_i32 s0, s0, 10
	s_add_i32 s0, s0, s2
	s_mul_hi_i32 s2, s1, 0x3e0f83e1
	s_lshr_b32 s3, s2, 31
	s_ashr_i32 s2, s2, 3
	s_add_i32 s2, s2, s3
	s_mul_i32 s2, s2, 33
	s_sub_i32 s1, s1, s2
	s_mul_i32 s34, s1, 0x7e
	s_sub_i32 s1, 1, s34
	s_max_i32 s8, s1, 0
	s_sub_i32 s1, 0x1001, s34
	s_add_i32 s21, s34, -1
	s_min_u32 s9, s1, 0x80
	s_ashr_i32 s1, s0, 31
	s_lshl_b64 s[18:19], s[0:1], 12
	s_ashr_i32 s3, s21, 31
	s_add_u32 s2, s18, s21
	s_addc_u32 s3, s19, s3
	s_lshl_b64 s[2:3], s[2:3], 11
	s_add_u32 s2, s72, s2
	v_mov_b32_e32 v133, v166
	s_addc_u32 s3, s73, s3
	s_ashr_i32 s61, s60, 31
	v_mov_b32_e32 v90, v166
	s_lshl_b64 s[4:5], s[60:61], 18
	v_readlane_b32 s6, v255, 24
	s_add_u32 s4, s6, s4
	v_ashrrev_i32_e32 v64, 3, v90
	v_readlane_b32 s6, v255, 25
	v_add_u32_e32 v9, 64, v64
	s_addc_u32 s5, s6, s5
	v_add_u32_e32 v10, 0x60, v64
	s_add_i32 s6, s9, -1
	v_max_i32_e32 v1, s8, v9
	v_add_u32_e32 v8, 32, v64
	v_max_i32_e32 v0, s8, v64
	v_min_u32_e32 v2, s6, v1
	v_max_i32_e32 v1, s8, v10
	v_min_u32_e32 v128, s6, v0
	v_max_i32_e32 v0, s8, v8
	v_min_u32_e32 v4, s6, v1
	v_lshlrev_b32_e32 v1, 4, v90
	v_min_u32_e32 v0, s6, v0
	v_lshlrev_b64 v[66:67], 11, v[128:129]
	v_and_b32_e32 v128, 0x70, v1
	v_mov_b32_e32 v1, v129
	v_lshlrev_b64 v[70:71], 11, v[0:1]
	v_mov_b32_e32 v3, v129
	v_lshl_add_u64 v[0:1], s[2:3], 0, v[70:71]
	v_lshlrev_b64 v[74:75], 11, v[2:3]
	v_mov_b32_e32 v5, v129
	v_lshl_add_u64 v[72:73], v[0:1], 0, v[128:129]
	v_lshl_add_u64 v[0:1], s[2:3], 0, v[74:75]
	v_lshlrev_b64 v[78:79], 11, v[4:5]
	v_lshl_add_u64 v[76:77], v[0:1], 0, v[128:129]
	v_lshl_add_u64 v[0:1], s[2:3], 0, v[78:79]
	v_ashrrev_i32_e32 v65, 31, v64
	v_lshl_add_u64 v[80:81], v[0:1], 0, v[128:129]
	v_lshlrev_b64 v[0:1], 11, v[64:65]
	v_lshl_add_u64 v[144:145], s[4:5], 0, v[0:1]
	v_lshl_add_u64 v[6:7], s[2:3], 0, v[66:67]
	v_lshl_add_u64 v[82:83], v[144:145], 0, v[128:129]
	s_mov_b32 s2, 0x10000
	v_add_co_u32_e32 v84, vcc, s2, v82
	s_mov_b32 s2, 0x20000
	s_nop 0
	v_addc_co_u32_e32 v85, vcc, 0, v83, vcc
	v_lshl_add_u64 v[68:69], v[6:7], 0, v[128:129]
	v_add_co_u32_e32 v86, vcc, s2, v82
	global_load_dwordx4 v[28:31], v[68:69], off
	global_load_dwordx4 v[36:39], v[72:73], off
	global_load_dwordx4 v[40:43], v[76:77], off
	global_load_dwordx4 v[44:47], v[80:81], off
	v_addc_co_u32_e32 v87, vcc, 0, v83, vcc
	s_mov_b32 s2, 0x30000
	v_add_co_u32_e32 v88, vcc, s2, v82
	global_load_dwordx4 v[48:51], v[82:83], off
	global_load_dwordx4 v[52:55], v[84:85], off
	v_addc_co_u32_e32 v89, vcc, 0, v83, vcc
	global_load_dwordx4 v[56:59], v[86:87], off
	global_load_dwordx4 v[60:63], v[88:89], off
	v_cmp_le_i32_e32 vcc, s8, v64
	v_cmp_gt_i32_e64 s[2:3], s9, v64
	s_and_b64 s[2:3], vcc, s[2:3]
	v_cmp_le_i32_e32 vcc, s8, v8
	v_cmp_gt_i32_e64 s[4:5], s9, v8
	s_and_b64 s[4:5], vcc, s[4:5]
	v_cmp_le_i32_e32 vcc, s8, v9
	v_cmp_gt_i32_e64 s[6:7], s9, v9
	v_lshlrev_b32_e32 v0, 3, v90
	s_and_b64 s[6:7], vcc, s[6:7]
	v_cmp_le_i32_e32 vcc, s8, v10
	v_cmp_gt_i32_e64 s[8:9], s9, v10
	v_lshrrev_b32_e32 v65, 4, v90
	v_bfe_u32 v91, v90, 4, 2
	s_and_b64 s[8:9], vcc, s[8:9]
	v_bitop3_b32 v92, v0, 56, v90 bitop3:0x48
	global_load_dwordx4 v[0:3], v[68:69], off offset:128
	global_load_dwordx4 v[4:7], v[72:73], off offset:128
	global_load_dwordx4 v[8:11], v[76:77], off offset:128
	global_load_dwordx4 v[12:15], v[80:81], off offset:128
	global_load_dwordx4 v[16:19], v[82:83], off offset:128
	global_load_dwordx4 v[20:23], v[84:85], off offset:128
	global_load_dwordx4 v[24:27], v[86:87], off offset:128
	global_load_dwordx4 v[32:35], v[88:89], off offset:128
	v_lshlrev_b32_e32 v92, 1, v92
	s_waitcnt lgkmcnt(0)
	s_barrier
; template <bool ATRANS = false, bool SWAP = true>
; DEV void gemm_seg(f32x4 (&acc)[4][4], bf16_t* As, bf16_t* Bs, const bf16_t* A, const bf16_t* B, int lda, int ldb,
;                   int K, int arow_lo, int arow_hi) {
;     ...
;   GLOAD(0, 0);
;   GLOAD(1, 1);
;   STAB(0, 0);
;   GLOAD(0, 2);
; DEV void acc_zero(f32x4 (&acc)[4][4]) {
; #pragma unroll
;   for (int m = 0; m < 4; ++m)
; #pragma unroll
;     for (int n = 0; n < 4; ++n) acc[m][n] = f32x4{0.f, 0.f, 0.f, 0.f};
	s_waitcnt vmcnt(15)
	v_cndmask_b32_e64 v28, 0, v28, s[2:3]
	v_cndmask_b32_e64 v29, 0, v29, s[2:3]
	v_cndmask_b32_e64 v30, 0, v30, s[2:3]
	v_cndmask_b32_e64 v31, 0, v31, s[2:3]
	v_lshl_or_b32 v135, v64, 7, v92
	ds_write_b128 v135, v[28:31]
	s_waitcnt vmcnt(14)
	v_cndmask_b32_e64 v28, 0, v36, s[4:5]
	v_cndmask_b32_e64 v29, 0, v37, s[4:5]
	v_cndmask_b32_e64 v30, 0, v38, s[4:5]
	v_cndmask_b32_e64 v31, 0, v39, s[4:5]
	ds_write_b128 v135, v[28:31] offset:4096
	s_waitcnt vmcnt(13)
	v_cndmask_b32_e64 v28, 0, v40, s[6:7]
	v_cndmask_b32_e64 v29, 0, v41, s[6:7]
	v_cndmask_b32_e64 v30, 0, v42, s[6:7]
	v_cndmask_b32_e64 v31, 0, v43, s[6:7]
	ds_write_b128 v135, v[28:31] offset:8192
	s_waitcnt vmcnt(12)
	v_cndmask_b32_e64 v28, 0, v44, s[8:9]
	v_cndmask_b32_e64 v29, 0, v45, s[8:9]
	v_cndmask_b32_e64 v30, 0, v46, s[8:9]
	v_cndmask_b32_e64 v31, 0, v47, s[8:9]
	ds_write_b128 v135, v[28:31] offset:12288
	s_waitcnt vmcnt(11)
	ds_write_b128 v135, v[48:51] offset:36864
	s_waitcnt vmcnt(10)
	ds_write_b128 v135, v[52:55] offset:40960
	s_waitcnt vmcnt(9)
	ds_write_b128 v135, v[56:59] offset:45056
	s_waitcnt vmcnt(8)
	ds_write_b128 v135, v[60:63] offset:49152
	s_waitcnt lgkmcnt(0)
	s_barrier
	global_load_dwordx4 v[28:31], v[68:69], off offset:256
	global_load_dwordx4 v[36:39], v[72:73], off offset:256
	global_load_dwordx4 v[40:43], v[76:77], off offset:256
	global_load_dwordx4 v[44:47], v[80:81], off offset:256
	global_load_dwordx4 v[48:51], v[82:83], off offset:256
	global_load_dwordx4 v[52:55], v[84:85], off offset:256
	global_load_dwordx4 v[56:59], v[86:87], off offset:256
	global_load_dwordx4 v[60:63], v[88:89], off offset:256
	v_and_b32_e32 v68, 7, v90
	v_lshlrev_b32_e32 v69, 7, v90
	s_ashr_i32 s35, s34, 31
	v_lshlrev_b32_e32 v64, 6, v90
	v_and_b32_e32 v72, 0x2000, v69
	v_bitop3_b32 v65, v65, v68, 3 bitop3:0x6c
	v_and_b32_e32 v69, 0x780, v69
	s_lshl_b64 s[0:1], s[0:1], 23
	s_lshl_b64 s[22:23], s[34:35], 11
	v_and_b32_e32 v64, 0xffffe000, v64
	v_lshl_or_b32 v65, v65, 4, v69
	s_add_u32 s22, s96, s22
	v_or_b32_e32 v139, v64, v65
	v_or_b32_e32 v164, v72, v65
	v_bitop3_b32 v65, v91, v68, 4 bitop3:0x36
	s_addc_u32 s23, s97, s23
	v_lshl_or_b32 v65, v65, 4, v69
	s_add_u32 s0, s22, s0
	v_or_b32_e32 v165, v64, v65
	s_addc_u32 s1, s23, s1
	v_mov_b32_e32 v64, 0
	v_add_u32_e32 v137, 0xd800, v135
	v_or_b32_e32 v207, v72, v65
	v_lshlrev_b32_e32 v128, 4, v68
	v_lshl_add_u64 v[146:147], s[0:1], 0, v[66:67]
	v_lshl_add_u64 v[148:149], s[0:1], 0, v[70:71]
	v_lshl_add_u64 v[150:151], s[0:1], 0, v[74:75]
	v_lshl_add_u64 v[152:153], s[0:1], 0, v[78:79]
	s_mov_b32 s22, -2
	v_mov_b32_e32 v65, v64
	v_mov_b32_e32 v66, v64
	v_mov_b32_e32 v67, v64
	v_mov_b32_e32 v68, v64
	v_mov_b32_e32 v69, v64
	v_mov_b32_e32 v70, v64
	v_mov_b32_e32 v71, v64
	v_mov_b32_e32 v72, v64
	v_mov_b32_e32 v73, v64
	v_mov_b32_e32 v74, v64
	v_mov_b32_e32 v75, v64
	v_mov_b32_e32 v76, v64
	v_mov_b32_e32 v77, v64
	v_mov_b32_e32 v78, v64
	v_mov_b32_e32 v79, v64
	v_mov_b32_e32 v80, v64
	v_mov_b32_e32 v81, v64
	v_mov_b32_e32 v82, v64
	v_mov_b32_e32 v83, v64
	v_mov_b32_e32 v84, v64
	v_mov_b32_e32 v85, v64
	v_mov_b32_e32 v86, v64
	v_mov_b32_e32 v87, v64
	v_mov_b32_e32 v88, v64
	v_mov_b32_e32 v89, v64
	v_mov_b32_e32 v90, v64
	v_mov_b32_e32 v91, v64
	v_mov_b32_e32 v92, v64
	v_mov_b32_e32 v93, v64
	v_mov_b32_e32 v94, v64
	v_mov_b32_e32 v95, v64
	v_mov_b32_e32 v96, v64
	v_mov_b32_e32 v97, v64
	v_mov_b32_e32 v98, v64
	v_mov_b32_e32 v99, v64
	v_mov_b32_e32 v100, v64
	v_mov_b32_e32 v101, v64
	v_mov_b32_e32 v102, v64
	v_mov_b32_e32 v103, v64
	v_mov_b32_e32 v104, v64
	v_mov_b32_e32 v105, v64
	v_mov_b32_e32 v106, v64
	v_mov_b32_e32 v107, v64
	v_mov_b32_e32 v108, v64
	v_mov_b32_e32 v109, v64
	v_mov_b32_e32 v110, v64
	v_mov_b32_e32 v111, v64
	v_mov_b32_e32 v112, v64
	v_mov_b32_e32 v113, v64
	v_mov_b32_e32 v114, v64
	v_mov_b32_e32 v115, v64
	v_mov_b32_e32 v116, v64
	v_mov_b32_e32 v117, v64
	v_mov_b32_e32 v118, v64
	v_mov_b32_e32 v119, v64
	v_mov_b32_e32 v120, v64
	v_mov_b32_e32 v121, v64
	v_mov_b32_e32 v122, v64
	v_mov_b32_e32 v123, v64
	v_mov_b32_e32 v124, v64
	v_mov_b32_e32 v125, v64
	v_mov_b32_e32 v126, v64
	v_mov_b32_e32 v127, v64
	s_branch .LBB0_824

; DEV int TID() { int t = threadIdx.x; asm volatile("" : "+v"(t)); return t; }
; DEV int BID() { int b = blockIdx.x; asm volatile("" : "+s"(b)); return b; }
; DEV int NBLK() { int b = gridDim.x; asm volatile("" : "+s"(b)); return b; }
; template <bool ATRANS = false, bool SWAP = true>
; DEV void gemm_seg(f32x4 (&acc)[4][4], bf16_t* As, bf16_t* Bs, const bf16_t* A, const bf16_t* B, int lda, int ldb,
;                   int K, int arow_lo, int arow_hi) {
;   const int tid = TID(), lane = tid & 63, wid = tid >> 6, wr = wid >> 1, wc = wid & 1;
;   const int fr = lane & 15, fq = lane >> 4;
;   const int lrow = tid >> 3, lk = (tid & 7) * 8;
;   const int tk = tid >> 4, trg = (tid & 15) * 8;
;   const bool av0 = (lrow >= arow_lo) && (lrow < arow_hi), av1 = (lrow + 32 >= arow_lo) && (lrow + 32 < arow_hi),
;              av2 = (lrow + 64 >= arow_lo) && (lrow + 64 < arow_hi), av3 = (lrow + 96 >= arow_lo) && (lrow + 96 < arow_hi);
;   const int c0 = min(max(lrow, arow_lo), arow_hi - 1), c1 = min(max(lrow + 32, arow_lo), arow_hi - 1),
;             c2 = min(max(lrow + 64, arow_lo), arow_hi - 1), c3 = min(max(lrow + 96, arow_lo), arow_hi - 1);
;   const bf16_t* a0 = ATRANS ? A + (long)(tk) * lda + trg : A + (long)c0 * lda + lk;
;   const bf16_t* a1 = ATRANS ? A + (long)(tk + 16) * lda + trg : A + (long)c1 * lda + lk;
;   const bf16_t* a2 = ATRANS ? A + (long)(tk + 32) * lda + trg : A + (long)c2 * lda + lk;
;   const bf16_t* a3 = ATRANS ? A + (long)(tk + 48) * lda + trg : A + (long)c3 * lda + lk;
;   const bf16_t* b0 = B + (long)lrow * ldb + lk;
;   const long bstep = 32L * ldb;
;   const long astep = ATRANS ? (long)lda : 1L;
;   uint4 A0a, A0b, A0c, A0d, B0a, B0b, B0c, B0d;
;   uint4 A1a, A1b, A1c, A1d, B1a, B1b, B1c, B1d;
;   const int so = lrow * LDT + lk;
;   const int sw = lrow * 64 + (((lk >> 3) ^ (lrow & 7)) * 8);
;   const int nk = K / BK;
;   const unsigned am0 = av0 ? 0xffffffffu : 0u, am1 = av1 ? 0xffffffffu : 0u, am2 = av2 ? 0xffffffffu : 0u,
;                  am3 = av3 ? 0xffffffffu : 0u;
; DEV void phase_down_pe(const Params& p, int layer, int grp, char* smem) {
;     ...
;   for (int it = BID(); it < nt; it += NBLK()) {
;     int tm, tn;
;     xcd_tile(it, tm, tn);
;     res_tile(p, layer, grp, tm, tn, p.ACT, DFF, p.WdownT + (long)layer * D * DFF, DFF, DFF, 0, smem);
.LBB0_872:
	s_ashr_i32 s20, s18, 3
	s_and_b32 s19, s18, 7
	s_and_b32 s0, s20, 0x1fffff8
	s_or_b32 s0, s0, s19
	v_mov_b32_e32 v80, v166
	s_lshl_b32 s22, s0, 7
	v_readlane_b32 s36, v254, 24
	s_bfe_u32 s21, s18, 0x30003
	v_ashrrev_i32_e32 v81, 3, v80
	s_ashr_i32 s23, s22, 31
	s_mul_i32 s0, s0, 0xb0000
	v_readlane_b32 s42, v254, 30
	v_max_i32_e32 v1, 0xffffffe0, v81
	s_mul_hi_i32 s1, s22, 0x1600
	v_readlane_b32 s43, v254, 31
	s_add_u32 s0, s42, s0
	v_med3_i32 v0, v81, 0, v204
	v_add_u32_e32 v1, 32, v1
	s_addc_u32 s1, s43, s1
	v_min_u32_e32 v1, 0x7f, v1
	v_max_i32_e32 v2, 0xffffffc0, v81
	v_mul_u32_u24_e32 v128, 0xb00, v0
	v_lshlrev_b32_e32 v0, 4, v80
	v_add_u32_e32 v2, 64, v2
	v_lshl_add_u64 v[144:145], v[128:129], 1, s[0:1]
	v_and_b32_e32 v128, 0x70, v0
	v_mul_u32_u24_e32 v0, 0xb00, v1
	v_min_u32_e32 v2, 0x7f, v2
	v_max_i32_e32 v3, 0xffffffa0, v81
	v_lshlrev_b32_e32 v0, 1, v0
	v_mov_b32_e32 v1, v129
	v_add_u32_e32 v3, 0x60, v3
	v_lshl_add_u64 v[146:147], s[0:1], 0, v[0:1]
	v_mul_u32_u24_e32 v0, 0xb00, v2
	s_mul_i32 s2, s21, 0xb0000
	v_readlane_b32 s3, v255, 26
	v_min_u32_e32 v3, 0x7f, v3
	v_lshlrev_b32_e32 v0, 1, v0
	s_add_u32 s2, s3, s2
	v_readlane_b32 s3, v255, 27
	v_lshl_add_u64 v[148:149], s[0:1], 0, v[0:1]
	v_mul_u32_u24_e32 v0, 0xb00, v3
	s_addc_u32 s3, s3, 0
	v_lshlrev_b32_e32 v0, 1, v0
	v_lshl_add_u64 v[150:151], s[0:1], 0, v[0:1]
	v_mov_b64_e32 v[0:1], s[2:3]
	v_mad_i64_i32 v[152:153], s[0:1], v81, s89, v[0:1]
	v_lshl_add_u64 v[72:73], v[152:153], 0, v[128:129]
	s_mov_b32 s0, 0x2c000
	v_add_co_u32_e32 v74, vcc, s0, v72
	s_mov_b32 s0, 0x58000
	s_nop 0
	v_addc_co_u32_e32 v75, vcc, 0, v73, vcc
	v_lshl_add_u64 v[64:65], v[144:145], 0, v[128:129]
	v_add_co_u32_e32 v76, vcc, s0, v72
	v_lshl_add_u64 v[66:67], v[146:147], 0, v[128:129]
	v_lshl_add_u64 v[68:69], v[148:149], 0, v[128:129]
	v_lshl_add_u64 v[70:71], v[150:151], 0, v[128:129]
	global_load_dwordx4 v[28:31], v[64:65], off
	global_load_dwordx4 v[36:39], v[66:67], off
	global_load_dwordx4 v[40:43], v[68:69], off
	global_load_dwordx4 v[44:47], v[70:71], off
	v_addc_co_u32_e32 v77, vcc, 0, v73, vcc
	s_mov_b32 s0, 0x84000
	v_add_co_u32_e32 v78, vcc, s0, v72
	global_load_dwordx4 v[48:51], v[72:73], off
	global_load_dwordx4 v[52:55], v[74:75], off
	v_addc_co_u32_e32 v79, vcc, 0, v73, vcc
	global_load_dwordx4 v[56:59], v[76:77], off
	global_load_dwordx4 v[60:63], v[78:79], off
	s_movk_i32 s0, 0x80
	v_add_u32_e32 v1, 32, v81
	v_cmp_gt_u32_e64 s[4:5], s0, v1
	v_add_u32_e32 v1, 64, v81
	v_lshlrev_b32_e32 v0, 3, v80
	v_cmp_gt_u32_e64 s[6:7], s0, v1
	v_add_u32_e32 v1, 0x60, v81
	v_lshrrev_b32_e32 v82, 4, v80
	v_bfe_u32 v83, v80, 4, 2
	v_cmp_gt_u32_e64 s[2:3], s0, v81
	v_cmp_gt_u32_e64 s[8:9], s0, v1
	s_mov_b32 s24, 0
	v_bitop3_b32 v84, v0, 56, v80 bitop3:0x48
	v_readlane_b32 s37, v254, 25
	v_readlane_b32 s38, v254, 26
	v_readlane_b32 s39, v254, 27
	v_readlane_b32 s40, v254, 28
	v_readlane_b32 s41, v254, 29
	v_readlane_b32 s44, v254, 32
	v_readlane_b32 s45, v254, 33
	v_readlane_b32 s46, v254, 34
	v_readlane_b32 s47, v254, 35
	v_readlane_b32 s48, v254, 36
	v_readlane_b32 s49, v254, 37
	v_readlane_b32 s50, v254, 38
	v_readlane_b32 s51, v254, 39
	global_load_dwordx4 v[0:3], v[64:65], off offset:128
	global_load_dwordx4 v[4:7], v[66:67], off offset:128
	global_load_dwordx4 v[8:11], v[68:69], off offset:128
	global_load_dwordx4 v[12:15], v[70:71], off offset:128
	global_load_dwordx4 v[16:19], v[72:73], off offset:128
	global_load_dwordx4 v[20:23], v[74:75], off offset:128
	global_load_dwordx4 v[24:27], v[76:77], off offset:128
	global_load_dwordx4 v[32:35], v[78:79], off offset:128
	v_lshlrev_b32_e32 v84, 1, v84
	s_waitcnt lgkmcnt(0)
	s_barrier
; template <bool ATRANS = false, bool SWAP = true>
; DEV void gemm_seg(f32x4 (&acc)[4][4], bf16_t* As, bf16_t* Bs, const bf16_t* A, const bf16_t* B, int lda, int ldb,
;                   int K, int arow_lo, int arow_hi) {
;     ...
;   GLOAD(0, 0);
;   GLOAD(1, 1);
;   STAB(0, 0);
;   GLOAD(0, 2);
; DEV void acc_zero(f32x4 (&acc)[4][4]) {
; #pragma unroll
;   for (int m = 0; m < 4; ++m)
; #pragma unroll
;     for (int n = 0; n < 4; ++n) acc[m][n] = f32x4{0.f, 0.f, 0.f, 0.f};
	s_waitcnt vmcnt(15)
	v_cndmask_b32_e64 v28, 0, v28, s[2:3]
	v_cndmask_b32_e64 v29, 0, v29, s[2:3]
	v_cndmask_b32_e64 v30, 0, v30, s[2:3]
	v_cndmask_b32_e64 v31, 0, v31, s[2:3]
	v_lshl_or_b32 v133, v81, 7, v84
	ds_write_b128 v133, v[28:31]
	s_waitcnt vmcnt(14)
	v_cndmask_b32_e64 v28, 0, v36, s[4:5]
	v_cndmask_b32_e64 v29, 0, v37, s[4:5]
	v_cndmask_b32_e64 v30, 0, v38, s[4:5]
	v_cndmask_b32_e64 v31, 0, v39, s[4:5]
	ds_write_b128 v133, v[28:31] offset:4096
	s_waitcnt vmcnt(13)
	v_cndmask_b32_e64 v28, 0, v40, s[6:7]
	v_cndmask_b32_e64 v29, 0, v41, s[6:7]
	v_cndmask_b32_e64 v30, 0, v42, s[6:7]
	v_cndmask_b32_e64 v31, 0, v43, s[6:7]
	ds_write_b128 v133, v[28:31] offset:8192
	s_waitcnt vmcnt(12)
	v_cndmask_b32_e64 v28, 0, v44, s[8:9]
	v_cndmask_b32_e64 v29, 0, v45, s[8:9]
	v_cndmask_b32_e64 v30, 0, v46, s[8:9]
	v_cndmask_b32_e64 v31, 0, v47, s[8:9]
	ds_write_b128 v133, v[28:31] offset:12288
	s_waitcnt vmcnt(11)
	ds_write_b128 v133, v[48:51] offset:36864
	s_waitcnt vmcnt(10)
	ds_write_b128 v133, v[52:55] offset:40960
	s_waitcnt vmcnt(9)
	ds_write_b128 v133, v[56:59] offset:45056
	s_waitcnt vmcnt(8)
	ds_write_b128 v133, v[60:63] offset:49152
	s_waitcnt lgkmcnt(0)
	s_barrier
	global_load_dwordx4 v[28:31], v[64:65], off offset:256
	global_load_dwordx4 v[36:39], v[66:67], off offset:256
	global_load_dwordx4 v[40:43], v[68:69], off offset:256
	global_load_dwordx4 v[44:47], v[70:71], off offset:256
	global_load_dwordx4 v[48:51], v[72:73], off offset:256
	global_load_dwordx4 v[52:55], v[74:75], off offset:256
	global_load_dwordx4 v[56:59], v[76:77], off offset:256
	global_load_dwordx4 v[60:63], v[78:79], off offset:256
	v_and_b32_e32 v65, 7, v80
	v_lshlrev_b32_e32 v66, 7, v80
	v_lshlrev_b32_e32 v64, 6, v80
	v_and_b32_e32 v67, 0x2000, v66
	v_bitop3_b32 v68, v82, v65, 3 bitop3:0x6c
	v_and_b32_e32 v66, 0x780, v66
	v_and_b32_e32 v64, 0xffffe000, v64
	v_lshl_or_b32 v68, v68, 4, v66
	v_or_b32_e32 v137, v64, v68
	v_or_b32_e32 v139, v67, v68
	v_bitop3_b32 v68, v83, v65, 4 bitop3:0x36
	v_lshl_or_b32 v66, v68, 4, v66
	v_or_b32_e32 v164, v64, v66
	v_mov_b32_e32 v64, 0
	v_add_u32_e32 v135, 0xd800, v133
	v_or_b32_e32 v165, v67, v66
	v_lshlrev_b32_e32 v128, 4, v65
	v_mov_b32_e32 v65, v64
	v_mov_b32_e32 v66, v64
	v_mov_b32_e32 v67, v64
	v_mov_b32_e32 v68, v64
	v_mov_b32_e32 v69, v64
	v_mov_b32_e32 v70, v64
	v_mov_b32_e32 v71, v64
	v_mov_b32_e32 v72, v64
	v_mov_b32_e32 v73, v64
	v_mov_b32_e32 v74, v64
	v_mov_b32_e32 v75, v64
	v_mov_b32_e32 v76, v64
	v_mov_b32_e32 v77, v64
	v_mov_b32_e32 v78, v64
	v_mov_b32_e32 v79, v64
	v_mov_b32_e32 v80, v64
	v_mov_b32_e32 v81, v64
	v_mov_b32_e32 v82, v64
	v_mov_b32_e32 v83, v64
	v_mov_b32_e32 v84, v64
	v_mov_b32_e32 v85, v64
	v_mov_b32_e32 v86, v64
	v_mov_b32_e32 v87, v64
	v_mov_b32_e32 v88, v64
	v_mov_b32_e32 v89, v64
	v_mov_b32_e32 v90, v64
	v_mov_b32_e32 v91, v64
	v_mov_b32_e32 v92, v64
	v_mov_b32_e32 v93, v64
	v_mov_b32_e32 v94, v64
	v_mov_b32_e32 v95, v64
	v_mov_b32_e32 v96, v64
	v_mov_b32_e32 v97, v64
	v_mov_b32_e32 v98, v64
	v_mov_b32_e32 v99, v64
	v_mov_b32_e32 v100, v64
	v_mov_b32_e32 v101, v64
	v_mov_b32_e32 v102, v64
	v_mov_b32_e32 v103, v64
	v_mov_b32_e32 v104, v64
	v_mov_b32_e32 v105, v64
	v_mov_b32_e32 v106, v64
	v_mov_b32_e32 v107, v64
	v_mov_b32_e32 v108, v64
	v_mov_b32_e32 v109, v64
	v_mov_b32_e32 v110, v64
	v_mov_b32_e32 v111, v64
	v_mov_b32_e32 v112, v64
	v_mov_b32_e32 v113, v64
	v_mov_b32_e32 v114, v64
	v_mov_b32_e32 v115, v64
	v_mov_b32_e32 v116, v64
	v_mov_b32_e32 v117, v64
	v_mov_b32_e32 v118, v64
	v_mov_b32_e32 v119, v64
	v_mov_b32_e32 v120, v64
	v_mov_b32_e32 v121, v64
	v_mov_b32_e32 v122, v64
	v_mov_b32_e32 v123, v64
	v_mov_b32_e32 v124, v64
	v_mov_b32_e32 v125, v64
	v_mov_b32_e32 v126, v64
	v_mov_b32_e32 v127, v64
	s_branch .LBB0_874

; DEV int BID() { int b = blockIdx.x; asm volatile("" : "+s"(b)); return b; }
; DEV int NBLK() { int b = gridDim.x; asm volatile("" : "+s"(b)); return b; }
; DEV uint2 pack4(float4 v) { uint2 o; o.x = pack2(v.x, v.y); o.y = pack2(v.z, v.w); return o; }
; DEV void res_epilogue(const Params& p, int layer, int grp, int r0, int tn, int mode, char* smem) {
;     ...
;   if (mode == 0 || mode == 3) {
;     const long grow0 = (long)grp * TG + r0;
;     const float* xsrc = (mode == 3 && layer == 0)
;                             ? ((grow0 < (long)NPROMPT * L) ? p.x_prompt + grow0 * D : p.x_sample + (grow0 - (long)NPROMPT * L) * D)
;                             : p.X + grow0 * D;
;     xsrc += tn * 128 + c4;
; #pragma unroll 4
;     for (int i = 0; i < 16; ++i) {
;       const int r = wid * 32 + i * 2 + rsub;
;       const long lrow = r0 + r;
;       float4 a = ld4(Cs + r * CS_LD + c4);
;       float4* x = (float4*)(p.X + ((long)grp * TG + lrow) * D + tn * 128 + c4);
;       float4 xv = *(const float4*)(xsrc + (long)r * D);
;       xv.x += a.x; xv.y += a.y; xv.z += a.z; xv.w += a.w;
;       *x = xv;
;       *(uint2*)(p.Hwk + lrow * D + tn * 128 + c4) = pack4(xv);
;       if (mode == 3) {
;         const float ss = half_sum(xv.x * xv.x + xv.y * xv.y + xv.z * xv.z + xv.w * xv.w);
;         if ((lane & 31) == 0) p.SSb[lrow * 8 + tn] = ss;
;       }
;     }
; DEV void phase_down_pe(const Params& p, int layer, int grp, char* smem) {
;     ...
;   for (int it = BID(); it < nt; it += NBLK()) {
;     int tm, tn;
;     xcd_tile(it, tm, tn);
;     res_tile(p, layer, grp, tm, tn, p.ACT, DFF, p.WdownT + (long)layer * D * DFF, DFF, DFF, 0, smem);
;   }
.LBB0_881:
	v_add_u32_e32 v6, s0, v12
	v_ashrrev_i32_e32 v7, 31, v6
	v_add_u32_e32 v8, s0, v10
	v_lshl_add_u64 v[14:15], s[12:13], 0, v[6:7]
	v_lshlrev_b64 v[14:15], 12, v[14:15]
	v_ashrrev_i32_e32 v9, 31, v8
	s_waitcnt vmcnt(2)
	v_lshl_add_u64 v[22:23], v[2:3], 0, v[14:15]
	v_lshlrev_b64 v[14:15], 12, v[8:9]
	v_lshl_add_u64 v[18:19], v[0:1], 0, v[14:15]
	global_load_dwordx4 v[18:21], v[18:19], off
	ds_read_b128 v[14:17], v11
	s_add_i32 s0, s0, 8
	s_cmp_lg_u32 s0, 32
	s_waitcnt vmcnt(0) lgkmcnt(0)
	v_pk_add_f32 v[14:15], v[14:15], v[18:19]
	v_pk_add_f32 v[16:17], v[16:17], v[20:21]
	v_and_b32_sdwa v9, v14, v172 dst_sel:DWORD dst_unused:UNUSED_PAD src0_sel:WORD_1 src1_sel:DWORD
	global_store_dwordx4 v[22:23], v[14:17], off
	v_add3_u32 v9, v14, v9, s86
	v_and_b32_sdwa v13, v17, v172 dst_sel:DWORD dst_unused:UNUSED_PAD src0_sel:WORD_1 src1_sel:DWORD
	v_and_b32_sdwa v14, v15, v172 dst_sel:DWORD dst_unused:UNUSED_PAD src0_sel:WORD_1 src1_sel:DWORD
	v_lshlrev_b64 v[18:19], 11, v[6:7]
	v_and_b32_sdwa v7, v16, v172 dst_sel:DWORD dst_unused:UNUSED_PAD src0_sel:WORD_1 src1_sel:DWORD
	v_add3_u32 v13, v17, v13, s86
	v_add3_u32 v14, v15, v14, s86
	v_add3_u32 v7, v16, v7, s86
	v_and_b32_e32 v13, 0xffff0000, v13
	v_and_b32_e32 v14, 0xffff0000, v14
	v_lshl_add_u64 v[18:19], v[4:5], 0, v[18:19]
	v_or_b32_sdwa v15, v13, v7 dst_sel:DWORD dst_unused:UNUSED_PAD src0_sel:DWORD src1_sel:WORD_1
	v_or_b32_sdwa v14, v14, v9 dst_sel:DWORD dst_unused:UNUSED_PAD src0_sel:DWORD src1_sel:WORD_1
	global_store_dwordx2 v[18:19], v[14:15], off
	v_add_u32_e32 v14, 2, v8
	v_ashrrev_i32_e32 v15, 31, v14
	v_lshlrev_b64 v[14:15], 12, v[14:15]
	v_lshl_add_u64 v[18:19], v[0:1], 0, v[14:15]
	global_load_dwordx4 v[18:21], v[18:19], off
	v_add_u32_e32 v22, 2, v6
	v_ashrrev_i32_e32 v23, 31, v22
	v_lshl_add_u64 v[16:17], s[12:13], 0, v[22:23]
	v_lshlrev_b64 v[16:17], 12, v[16:17]
	v_lshl_add_u64 v[24:25], v[2:3], 0, v[16:17]
	ds_read_b128 v[14:17], v11 offset:1056
	s_waitcnt vmcnt(0) lgkmcnt(0)
	v_pk_add_f32 v[14:15], v[14:15], v[18:19]
	v_pk_add_f32 v[16:17], v[16:17], v[20:21]
	v_and_b32_sdwa v9, v14, v172 dst_sel:DWORD dst_unused:UNUSED_PAD src0_sel:WORD_1 src1_sel:DWORD
	global_store_dwordx4 v[24:25], v[14:17], off
	v_add3_u32 v9, v14, v9, s86
	v_and_b32_sdwa v13, v17, v172 dst_sel:DWORD dst_unused:UNUSED_PAD src0_sel:WORD_1 src1_sel:DWORD
	v_and_b32_sdwa v14, v15, v172 dst_sel:DWORD dst_unused:UNUSED_PAD src0_sel:WORD_1 src1_sel:DWORD
	v_and_b32_sdwa v7, v16, v172 dst_sel:DWORD dst_unused:UNUSED_PAD src0_sel:WORD_1 src1_sel:DWORD
	v_add3_u32 v13, v17, v13, s86
	v_add3_u32 v14, v15, v14, s86
	v_lshlrev_b64 v[18:19], 11, v[22:23]
	v_add3_u32 v7, v16, v7, s86
	v_and_b32_e32 v13, 0xffff0000, v13
	v_and_b32_e32 v14, 0xffff0000, v14
	v_lshl_add_u64 v[18:19], v[4:5], 0, v[18:19]
	v_or_b32_sdwa v15, v13, v7 dst_sel:DWORD dst_unused:UNUSED_PAD src0_sel:DWORD src1_sel:WORD_1
	v_or_b32_sdwa v14, v14, v9 dst_sel:DWORD dst_unused:UNUSED_PAD src0_sel:DWORD src1_sel:WORD_1
	global_store_dwordx2 v[18:19], v[14:15], off
	v_add_u32_e32 v14, 4, v8
	v_ashrrev_i32_e32 v15, 31, v14
	v_lshlrev_b64 v[14:15], 12, v[14:15]
	v_lshl_add_u64 v[18:19], v[0:1], 0, v[14:15]
	global_load_dwordx4 v[18:21], v[18:19], off
	v_add_u32_e32 v22, 4, v6
	v_ashrrev_i32_e32 v23, 31, v22
	v_lshl_add_u64 v[16:17], s[12:13], 0, v[22:23]
	v_lshlrev_b64 v[16:17], 12, v[16:17]
	v_lshl_add_u64 v[24:25], v[2:3], 0, v[16:17]
	ds_read_b128 v[14:17], v11 offset:2112
	v_add_u32_e32 v8, 6, v8
	s_waitcnt vmcnt(0) lgkmcnt(0)
	v_pk_add_f32 v[14:15], v[14:15], v[18:19]
	v_pk_add_f32 v[16:17], v[16:17], v[20:21]
	v_and_b32_sdwa v9, v14, v172 dst_sel:DWORD dst_unused:UNUSED_PAD src0_sel:WORD_1 src1_sel:DWORD
	global_store_dwordx4 v[24:25], v[14:17], off
	v_add3_u32 v9, v14, v9, s86
	v_and_b32_sdwa v13, v17, v172 dst_sel:DWORD dst_unused:UNUSED_PAD src0_sel:WORD_1 src1_sel:DWORD
	v_and_b32_sdwa v14, v15, v172 dst_sel:DWORD dst_unused:UNUSED_PAD src0_sel:WORD_1 src1_sel:DWORD
	v_and_b32_sdwa v7, v16, v172 dst_sel:DWORD dst_unused:UNUSED_PAD src0_sel:WORD_1 src1_sel:DWORD
	v_add3_u32 v13, v17, v13, s86
	v_add3_u32 v14, v15, v14, s86
	v_lshlrev_b64 v[18:19], 11, v[22:23]
	v_add3_u32 v7, v16, v7, s86
	v_and_b32_e32 v13, 0xffff0000, v13
	v_and_b32_e32 v14, 0xffff0000, v14
	v_lshl_add_u64 v[18:19], v[4:5], 0, v[18:19]
	v_or_b32_sdwa v15, v13, v7 dst_sel:DWORD dst_unused:UNUSED_PAD src0_sel:DWORD src1_sel:WORD_1
	v_or_b32_sdwa v14, v14, v9 dst_sel:DWORD dst_unused:UNUSED_PAD src0_sel:DWORD src1_sel:WORD_1
	global_store_dwordx2 v[18:19], v[14:15], off
	v_add_u32_e32 v18, 6, v6
	v_ashrrev_i32_e32 v19, 31, v18
	v_lshl_add_u64 v[6:7], s[12:13], 0, v[18:19]
	v_lshlrev_b64 v[6:7], 12, v[6:7]
	v_ashrrev_i32_e32 v9, 31, v8
	v_lshl_add_u64 v[20:21], v[2:3], 0, v[6:7]
	v_lshlrev_b64 v[6:7], 12, v[8:9]
	v_lshl_add_u64 v[14:15], v[0:1], 0, v[6:7]
	global_load_dwordx4 v[14:17], v[14:15], off
	ds_read_b128 v[6:9], v11 offset:3168
	v_add_u32_e32 v11, 0x1080, v11
	s_waitcnt vmcnt(0) lgkmcnt(0)
	v_pk_add_f32 v[6:7], v[6:7], v[14:15]
	v_pk_add_f32 v[8:9], v[8:9], v[16:17]
	v_and_b32_sdwa v16, v6, v172 dst_sel:DWORD dst_unused:UNUSED_PAD src0_sel:WORD_1 src1_sel:DWORD
	v_and_b32_sdwa v13, v8, v172 dst_sel:DWORD dst_unused:UNUSED_PAD src0_sel:WORD_1 src1_sel:DWORD
	global_store_dwordx4 v[20:21], v[6:9], off
	v_lshlrev_b64 v[14:15], 11, v[18:19]
	v_lshl_add_u64 v[14:15], v[4:5], 0, v[14:15]
	v_add3_u32 v6, v6, v16, s86
	v_add3_u32 v8, v8, v13, s86
	v_and_b32_sdwa v13, v9, v172 dst_sel:DWORD dst_unused:UNUSED_PAD src0_sel:WORD_1 src1_sel:DWORD
	v_and_b32_sdwa v16, v7, v172 dst_sel:DWORD dst_unused:UNUSED_PAD src0_sel:WORD_1 src1_sel:DWORD
	v_add3_u32 v9, v9, v13, s86
	v_add3_u32 v7, v7, v16, s86
	v_and_b32_e32 v9, 0xffff0000, v9
	v_and_b32_e32 v13, 0xffff0000, v7
	v_or_b32_sdwa v7, v9, v8 dst_sel:DWORD dst_unused:UNUSED_PAD src0_sel:DWORD src1_sel:WORD_1
	v_or_b32_sdwa v6, v13, v6 dst_sel:DWORD dst_unused:UNUSED_PAD src0_sel:DWORD src1_sel:WORD_1
	global_store_dwordx2 v[14:15], v[6:7], off
	s_cbranch_scc1 .LBB0_881
	v_readlane_b32 s24, v253, 0
	v_readlane_b32 s30, v253, 6
	s_mov_b32 s0, s30
	s_add_i32 s18, s0, s18
	v_readlane_b32 s28, v253, 4
	v_readlane_b32 s29, v253, 5
	s_cmpk_lt_i32 s18, 0xa00
	v_readlane_b32 s25, v253, 1
	v_readlane_b32 s26, v253, 2
	v_readlane_b32 s27, v253, 3
	v_readlane_b32 s31, v253, 7
	s_cbranch_scc1 .LBB0_872

; DEV int TID() { int t = threadIdx.x; asm volatile("" : "+v"(t)); return t; }
; DEV int BID() { int b = blockIdx.x; asm volatile("" : "+s"(b)); return b; }
; DEV int NBLK() { int b = gridDim.x; asm volatile("" : "+s"(b)); return b; }
; template <bool ATRANS = false, bool SWAP = true>
; DEV void gemm_seg(f32x4 (&acc)[4][4], bf16_t* As, bf16_t* Bs, const bf16_t* A, const bf16_t* B, int lda, int ldb,
;                   int K, int arow_lo, int arow_hi) {
;   const int tid = TID(), lane = tid & 63, wid = tid >> 6, wr = wid >> 1, wc = wid & 1;
;   const int fr = lane & 15, fq = lane >> 4;
;   const int lrow = tid >> 3, lk = (tid & 7) * 8;
;   const int tk = tid >> 4, trg = (tid & 15) * 8;
;   const bool av0 = (lrow >= arow_lo) && (lrow < arow_hi), av1 = (lrow + 32 >= arow_lo) && (lrow + 32 < arow_hi),
;              av2 = (lrow + 64 >= arow_lo) && (lrow + 64 < arow_hi), av3 = (lrow + 96 >= arow_lo) && (lrow + 96 < arow_hi);
;   const int c0 = min(max(lrow, arow_lo), arow_hi - 1), c1 = min(max(lrow + 32, arow_lo), arow_hi - 1),
;             c2 = min(max(lrow + 64, arow_lo), arow_hi - 1), c3 = min(max(lrow + 96, arow_lo), arow_hi - 1);
;   const bf16_t* a0 = ATRANS ? A + (long)(tk) * lda + trg : A + (long)c0 * lda + lk;
;   const bf16_t* a1 = ATRANS ? A + (long)(tk + 16) * lda + trg : A + (long)c1 * lda + lk;
;   const bf16_t* a2 = ATRANS ? A + (long)(tk + 32) * lda + trg : A + (long)c2 * lda + lk;
;   const bf16_t* a3 = ATRANS ? A + (long)(tk + 48) * lda + trg : A + (long)c3 * lda + lk;
;   const bf16_t* b0 = B + (long)lrow * ldb + lk;
;   const long bstep = 32L * ldb;
;   const long astep = ATRANS ? (long)lda : 1L;
;   uint4 A0a, A0b, A0c, A0d, B0a, B0b, B0c, B0d;
;   uint4 A1a, A1b, A1c, A1d, B1a, B1b, B1c, B1d;
;   const int so = lrow * LDT + lk;
;   const int sw = lrow * 64 + (((lk >> 3) ^ (lrow & 7)) * 8);
;   const int nk = K / BK;
;   const unsigned am0 = av0 ? 0xffffffffu : 0u, am1 = av1 ? 0xffffffffu : 0u, am2 = av2 ? 0xffffffffu : 0u,
;                  am3 = av3 ? 0xffffffffu : 0u;
; DEV void phase_plegate(const Params& p, int layer, int grp, char* smem) {
;     ...
;   for (int it = BID(); it < ntiles; it += NBLK()) {
;     int tm, tn;
;     xcd_tile(it, tm, tn);
;     res_tile(p, layer, grp, tm, tn, p.Hwk, D, p.PleGateT + (long)layer * D * D, D, D, 2, smem);
.LBB0_921:
	s_mov_b32 s0, s30
	s_add_i32 s18, s0, s18
	s_cmpk_lt_i32 s18, 0xa00
	s_cbranch_scc0 .LBB0_917
.LBB0_922:
	s_ashr_i32 s20, s18, 3
	s_and_b32 s19, s18, 7
	s_and_b32 s0, s20, 0x1fffff8
	s_or_b32 s0, s0, s19
	s_lshl_b32 s0, s0, 7
	v_mov_b32_e32 v82, v166
	s_ashr_i32 s1, s0, 31
	s_bfe_u32 s21, s18, 0x30003
	v_ashrrev_i32_e32 v64, 3, v82
	s_lshl_b64 s[0:1], s[0:1], 11
	v_max_i32_e32 v1, 0xffffffe0, v64
	s_add_u32 s0, s72, s0
	v_med3_i32 v0, v64, 0, v204
	v_add_u32_e32 v1, 32, v1
	v_max_i32_e32 v2, 0xffffffc0, v64
	s_addc_u32 s1, s73, s1
	v_min_u32_e32 v1, 0x7f, v1
	v_add_u32_e32 v2, 64, v2
	v_max_i32_e32 v3, 0xffffffa0, v64
	v_lshlrev_b32_e32 v128, 11, v0
	v_lshlrev_b32_e32 v0, 4, v82
	v_min_u32_e32 v2, 0x7f, v2
	v_add_u32_e32 v3, 0x60, v3
	v_lshl_add_u64 v[144:145], s[0:1], 0, v[128:129]
	v_and_b32_e32 v128, 0x70, v0
	v_lshlrev_b32_e32 v0, 11, v1
	v_mov_b32_e32 v1, v129
	s_lshl_b32 s2, s21, 18
	v_readlane_b32 s3, v255, 28
	v_min_u32_e32 v3, 0x7f, v3
	v_lshl_add_u64 v[146:147], s[0:1], 0, v[0:1]
	v_lshlrev_b32_e32 v0, 11, v2
	s_add_u32 s2, s3, s2
	v_readlane_b32 s3, v255, 29
	v_lshl_add_u64 v[148:149], s[0:1], 0, v[0:1]
	v_lshlrev_b32_e32 v0, 11, v3
	v_ashrrev_i32_e32 v65, 31, v64
	s_addc_u32 s3, s3, 0
	v_lshl_add_u64 v[150:151], s[0:1], 0, v[0:1]
	v_lshlrev_b64 v[0:1], 11, v[64:65]
	v_lshl_add_u64 v[152:153], s[2:3], 0, v[0:1]
	v_lshl_add_u64 v[74:75], v[152:153], 0, v[128:129]
	s_mov_b32 s0, 0x10000
	v_add_co_u32_e32 v76, vcc, s0, v74
	s_mov_b32 s0, 0x20000
	s_nop 0
	v_addc_co_u32_e32 v77, vcc, 0, v75, vcc
	v_lshl_add_u64 v[66:67], v[144:145], 0, v[128:129]
	v_add_co_u32_e32 v78, vcc, s0, v74
	v_lshl_add_u64 v[68:69], v[146:147], 0, v[128:129]
	v_lshl_add_u64 v[70:71], v[148:149], 0, v[128:129]
	v_lshl_add_u64 v[72:73], v[150:151], 0, v[128:129]
	global_load_dwordx4 v[28:31], v[66:67], off
	global_load_dwordx4 v[36:39], v[68:69], off
	global_load_dwordx4 v[40:43], v[70:71], off
	global_load_dwordx4 v[44:47], v[72:73], off
	v_addc_co_u32_e32 v79, vcc, 0, v75, vcc
	s_mov_b32 s0, 0x30000
	v_add_co_u32_e32 v80, vcc, s0, v74
	global_load_dwordx4 v[48:51], v[74:75], off
	global_load_dwordx4 v[52:55], v[76:77], off
	v_addc_co_u32_e32 v81, vcc, 0, v75, vcc
	global_load_dwordx4 v[56:59], v[78:79], off
	global_load_dwordx4 v[60:63], v[80:81], off
	s_movk_i32 s0, 0x80
	v_add_u32_e32 v1, 32, v64
	v_cmp_gt_u32_e64 s[4:5], s0, v1
	v_add_u32_e32 v1, 64, v64
	v_lshlrev_b32_e32 v0, 3, v82
	v_cmp_gt_u32_e64 s[6:7], s0, v1
	v_add_u32_e32 v1, 0x60, v64
	v_lshrrev_b32_e32 v65, 4, v82
	v_bfe_u32 v83, v82, 4, 2
	v_cmp_gt_u32_e64 s[2:3], s0, v64
	v_cmp_gt_u32_e64 s[8:9], s0, v1
	s_mov_b32 s22, 0
	v_bitop3_b32 v84, v0, 56, v82 bitop3:0x48
	global_load_dwordx4 v[0:3], v[66:67], off offset:128
	global_load_dwordx4 v[4:7], v[68:69], off offset:128
	global_load_dwordx4 v[8:11], v[70:71], off offset:128
	global_load_dwordx4 v[12:15], v[72:73], off offset:128
	global_load_dwordx4 v[16:19], v[74:75], off offset:128
	global_load_dwordx4 v[20:23], v[76:77], off offset:128
	global_load_dwordx4 v[24:27], v[78:79], off offset:128
	global_load_dwordx4 v[32:35], v[80:81], off offset:128
	v_lshlrev_b32_e32 v84, 1, v84
	s_waitcnt lgkmcnt(0)
	s_barrier
	s_waitcnt vmcnt(15)
	v_cndmask_b32_e64 v28, 0, v28, s[2:3]
	v_cndmask_b32_e64 v29, 0, v29, s[2:3]
	v_cndmask_b32_e64 v30, 0, v30, s[2:3]
	v_cndmask_b32_e64 v31, 0, v31, s[2:3]
	v_lshl_or_b32 v133, v64, 7, v84
	ds_write_b128 v133, v[28:31]
	s_waitcnt vmcnt(14)
	v_cndmask_b32_e64 v28, 0, v36, s[4:5]
	v_cndmask_b32_e64 v29, 0, v37, s[4:5]
	v_cndmask_b32_e64 v30, 0, v38, s[4:5]
	v_cndmask_b32_e64 v31, 0, v39, s[4:5]
	ds_write_b128 v133, v[28:31] offset:4096
	s_waitcnt vmcnt(13)
	v_cndmask_b32_e64 v28, 0, v40, s[6:7]
	v_cndmask_b32_e64 v29, 0, v41, s[6:7]
	v_cndmask_b32_e64 v30, 0, v42, s[6:7]
	v_cndmask_b32_e64 v31, 0, v43, s[6:7]
	ds_write_b128 v133, v[28:31] offset:8192
	s_waitcnt vmcnt(12)
	v_cndmask_b32_e64 v28, 0, v44, s[8:9]
	v_cndmask_b32_e64 v29, 0, v45, s[8:9]
	v_cndmask_b32_e64 v30, 0, v46, s[8:9]
	v_cndmask_b32_e64 v31, 0, v47, s[8:9]
	ds_write_b128 v133, v[28:31] offset:12288
	s_waitcnt vmcnt(11)
	ds_write_b128 v133, v[48:51] offset:36864
	s_waitcnt vmcnt(10)
	ds_write_b128 v133, v[52:55] offset:40960
	s_waitcnt vmcnt(9)
	ds_write_b128 v133, v[56:59] offset:45056
	s_waitcnt vmcnt(8)
	ds_write_b128 v133, v[60:63] offset:49152
	s_waitcnt lgkmcnt(0)
	s_barrier
	global_load_dwordx4 v[28:31], v[66:67], off offset:256
	global_load_dwordx4 v[36:39], v[68:69], off offset:256
	global_load_dwordx4 v[40:43], v[70:71], off offset:256
	global_load_dwordx4 v[44:47], v[72:73], off offset:256
	global_load_dwordx4 v[48:51], v[74:75], off offset:256
	global_load_dwordx4 v[52:55], v[76:77], off offset:256
	global_load_dwordx4 v[56:59], v[78:79], off offset:256
	global_load_dwordx4 v[60:63], v[80:81], off offset:256
	v_and_b32_e32 v66, 7, v82
	v_lshlrev_b32_e32 v67, 7, v82
	v_lshlrev_b32_e32 v64, 6, v82
	v_and_b32_e32 v68, 0x2000, v67
	v_bitop3_b32 v65, v65, v66, 3 bitop3:0x6c
	v_and_b32_e32 v67, 0x780, v67
	v_and_b32_e32 v64, 0xffffe000, v64
	v_lshl_or_b32 v65, v65, 4, v67
	v_or_b32_e32 v137, v64, v65
	v_or_b32_e32 v139, v68, v65
	v_bitop3_b32 v65, v83, v66, 4 bitop3:0x36
	v_lshl_or_b32 v65, v65, 4, v67
	v_or_b32_e32 v164, v64, v65
	v_mov_b32_e32 v64, 0
	v_add_u32_e32 v135, 0xd800, v133
	v_or_b32_e32 v165, v68, v65
	v_lshlrev_b32_e32 v128, 4, v66
	v_mov_b32_e32 v65, v64
	v_mov_b32_e32 v66, v64
	v_mov_b32_e32 v67, v64
	v_mov_b32_e32 v68, v64
	v_mov_b32_e32 v69, v64
	v_mov_b32_e32 v70, v64
	v_mov_b32_e32 v71, v64
	v_mov_b32_e32 v72, v64
	v_mov_b32_e32 v73, v64
	v_mov_b32_e32 v74, v64
	v_mov_b32_e32 v75, v64
	v_mov_b32_e32 v76, v64
	v_mov_b32_e32 v77, v64
	v_mov_b32_e32 v78, v64
	v_mov_b32_e32 v79, v64
	v_mov_b32_e32 v80, v64
	v_mov_b32_e32 v81, v64
	v_mov_b32_e32 v82, v64
	v_mov_b32_e32 v83, v64
	v_mov_b32_e32 v84, v64
	v_mov_b32_e32 v85, v64
	v_mov_b32_e32 v86, v64
	v_mov_b32_e32 v87, v64
	v_mov_b32_e32 v88, v64
	v_mov_b32_e32 v89, v64
	v_mov_b32_e32 v90, v64
	v_mov_b32_e32 v91, v64
	v_mov_b32_e32 v92, v64
	v_mov_b32_e32 v93, v64
	v_mov_b32_e32 v94, v64
	v_mov_b32_e32 v95, v64
	v_mov_b32_e32 v96, v64
	v_mov_b32_e32 v97, v64
	v_mov_b32_e32 v98, v64
	v_mov_b32_e32 v99, v64
	v_mov_b32_e32 v100, v64
	v_mov_b32_e32 v101, v64
	v_mov_b32_e32 v102, v64
	v_mov_b32_e32 v103, v64
	v_mov_b32_e32 v104, v64
	v_mov_b32_e32 v105, v64
	v_mov_b32_e32 v106, v64
	v_mov_b32_e32 v107, v64
	v_mov_b32_e32 v108, v64
	v_mov_b32_e32 v109, v64
	v_mov_b32_e32 v110, v64
	v_mov_b32_e32 v111, v64
	v_mov_b32_e32 v112, v64
	v_mov_b32_e32 v113, v64
	v_mov_b32_e32 v114, v64
	v_mov_b32_e32 v115, v64
	v_mov_b32_e32 v116, v64
	v_mov_b32_e32 v117, v64
	v_mov_b32_e32 v118, v64
	v_mov_b32_e32 v119, v64
	v_mov_b32_e32 v120, v64
	v_mov_b32_e32 v121, v64
	v_mov_b32_e32 v122, v64
	v_mov_b32_e32 v123, v64
	v_mov_b32_e32 v124, v64
	v_mov_b32_e32 v125, v64
	v_mov_b32_e32 v126, v64
	v_mov_b32_e32 v127, v64
	s_branch .LBB0_924
